# GEMM main loop first load segment: ds_reads and DMA issue moved ahead of the pointer/select SALU
# speedup vs baseline: 1.0054x; 1.0054x over previous
; #define PG8_STAGE(bufoff, gbase, voff) do { _Pragma("unroll") for (int _i = 0; _i < 2; ++_i) \
;         __builtin_amdgcn_global_load_lds((const unsigned*)((const char*)(gbase) + (voff)[_i]), (LAS unsigned*)(lds + (bufoff) + ldsw + _i * 8192), 16, 0, 0); } while (0)
; #define PG8_LDA(dst, b, h) do { _Pragma("unroll") for (int m = 0; m < 4; ++m) _Pragma("unroll") for (int k = 0; k < 2; ++k) dst[m][k] = *(const LAS bf16x8*)(lds + PG8_SA(b, h) + aoff + m * 2048 + k * 1024); } while (0)
; #define PG8_LDB(dst, b, h) do { _Pragma("unroll") for (int n = 0; n < 2; ++n) _Pragma("unroll") for (int k = 0; k < 2; ++k) dst[n][k] = *(const LAS bf16x8*)(lds + PG8_SB(b, h) + boff + n * 2048 + k * 1024); } while (0)
; #define PG8_MMA(ai, bj, At, Bt) do { __builtin_amdgcn_s_setprio(1); _Pragma("unroll") for (int m = 0; m < 4; ++m) _Pragma("unroll") for (int n = 0; n < 2; ++n) _Pragma("unroll") for (int k = 0; k < 2; ++k) \
;         acc[ai][bj][m][n] = __builtin_amdgcn_mfma_f32_16x16x32_bf16(Bt[n][k], At[m][k], acc[ai][bj][m][n], 0, 0, 0); __builtin_amdgcn_s_setprio(0); } while (0)
; #define PG8_WAIT_V(n) asm volatile("s_waitcnt vmcnt(" #n ")" ::: "memory")
; #define PG8_WAIT_L(n) asm volatile("s_waitcnt lgkmcnt(" #n ")" ::: "memory")
; #define PG8_BAR __builtin_amdgcn_s_barrier()
; #define PG8_SCHED __builtin_amdgcn_sched_barrier(0)
; __device__ __forceinline__ void gemm_phase(LAS unsigned char* lds, const GemmD g, const Sched& S, const Epi& E) {
;     ...
;         for (int t = 0; t < nt; t += 2) {
;             const bool last = (t == nt - 2);
;             const char* a1 = cA + (size_t)(t + 1) * kstep;
;             const char* a2 = last ? nA : cA + (size_t)(t + 2) * kstep; const char* b2 = last ? nB : cB + (size_t)(t + 2) * kstep;
;             const char* a3 = a2 + kstep; const char* b3 = b2 + kstep;
;             PG8_LDB(B0, 0, 0); PG8_LDB(B1, 0, 1); PG8_SCHED; PG8_LDA(At, 0, 0); PG8_STAGE(PG8_SA(1, 1), a1 + hstepA, voffA);
;             PG8_WAIT_V(8); PG8_WAIT_L(0); PG8_BAR; PG8_MMA(0, 0, At, B0); PG8_MMA(0, 1, At, B1); PG8_BAR; PG8_SCHED;
;             PG8_LDA(At, 0, 1); PG8_STAGE(PG8_SB(0, 0), b2, voffB); PG8_STAGE(PG8_SB(0, 1), b2 + hstepB, voffB); PG8_STAGE(PG8_SA(0, 0), a2, voffA);
;             PG8_WAIT_V(8); PG8_WAIT_L(0); PG8_BAR; PG8_MMA(1, 0, At, B0); PG8_MMA(1, 1, At, B1); PG8_BAR; PG8_SCHED;
.Lprio_done:
	v_add_u32_e32 v240, 0x10000, v160
	v_add_u32_e32 v241, 0x14000, v160
	v_add_u32_e32 v242, 0x18000, v160
	v_add_u32_e32 v243, 0x1c000, v160
	ds_read_b128 v[130:133], v240
	ds_read_b128 v[146:149], v240 offset:1024
	ds_read_b128 v[150:153], v240 offset:2048
	ds_read_b128 v[154:157], v240 offset:3072
	ds_read_b128 v[162:165], v241
	ds_read_b128 v[166:169], v241 offset:1024
	ds_read_b128 v[170:173], v241 offset:2048
	ds_read_b128 v[174:177], v241 offset:3072
	s_add_i32 m0, s31, 0xc000
	ds_read_b128 v[182:185], v161
	ds_read_b128 v[186:189], v161 offset:1024
	ds_read_b128 v[190:193], v161 offset:2048
	ds_read_b128 v[216:219], v161 offset:3072
	ds_read_b128 v[220:223], v161 offset:4096
	ds_read_b128 v[224:227], v161 offset:5120
	ds_read_b128 v[228:231], v161 offset:6144
	ds_read_b128 v[236:239], v161 offset:7168
	global_load_lds_dwordx4 v142, s[8:9]
	s_add_i32 m0, s31, 0xe000
	s_nop 0
	global_load_lds_dwordx4 v144, s[8:9]
	s_add_i32 s92, s26, 2
	s_add_u32 s93, s8, 0x80
	s_addc_u32 s27, s9, 0
	s_add_i32 s22, 0, 0x10000
	s_cmp_eq_u32 s11, s26
	s_cselect_b32 s27, s1, s27
	s_cselect_b32 s26, s0, s93
	s_cselect_b32 vcc_hi, s17, s35
	s_cselect_b32 vcc_lo, s16, s34
	s_add_i32 s23, 0, 0x14000
	s_waitcnt vmcnt(8)
	s_waitcnt lgkmcnt(0)
	s_barrier
	s_waitcnt lgkmcnt(0)
	v_mfma_f32_16x16x32_bf16 v[126:129], v[130:133], v[182:185], 0
	v_mfma_f32_16x16x32_bf16 v[122:125], v[150:153], v[182:185], 0
	v_mfma_f32_16x16x32_bf16 v[110:113], v[130:133], v[190:193], 0
	v_mfma_f32_16x16x32_bf16 v[106:109], v[150:153], v[190:193], 0
	v_mfma_f32_16x16x32_bf16 v[94:97], v[130:133], v[220:223], 0
	v_mfma_f32_16x16x32_bf16 v[90:93], v[150:153], v[220:223], 0
	v_mfma_f32_16x16x32_bf16 v[78:81], v[130:133], v[228:231], 0
	v_mfma_f32_16x16x32_bf16 v[74:77], v[150:153], v[228:231], 0
	v_mfma_f32_16x16x32_bf16 v[126:129], v[146:149], v[186:189], v[126:129]
	v_mfma_f32_16x16x32_bf16 v[122:125], v[154:157], v[186:189], v[122:125]
	v_mfma_f32_16x16x32_bf16 v[110:113], v[146:149], v[216:219], v[110:113]
	v_mfma_f32_16x16x32_bf16 v[106:109], v[154:157], v[216:219], v[106:109]
	v_mfma_f32_16x16x32_bf16 v[94:97], v[146:149], v[224:227], v[94:97]
	v_mfma_f32_16x16x32_bf16 v[90:93], v[154:157], v[224:227], v[90:93]
	v_mfma_f32_16x16x32_bf16 v[78:81], v[146:149], v[236:239], v[78:81]
	v_mfma_f32_16x16x32_bf16 v[74:77], v[154:157], v[236:239], v[74:77]
	v_mfma_f32_16x16x32_bf16 v[118:121], v[162:165], v[182:185], 0
	v_mfma_f32_16x16x32_bf16 v[114:117], v[170:173], v[182:185], 0
	v_mfma_f32_16x16x32_bf16 v[102:105], v[162:165], v[190:193], 0
	v_mfma_f32_16x16x32_bf16 v[98:101], v[170:173], v[190:193], 0
	v_mfma_f32_16x16x32_bf16 v[86:89], v[162:165], v[220:223], 0
	v_mfma_f32_16x16x32_bf16 v[82:85], v[170:173], v[220:223], 0
	v_mfma_f32_16x16x32_bf16 v[70:73], v[162:165], v[228:231], 0
	v_mfma_f32_16x16x32_bf16 v[66:69], v[170:173], v[228:231], 0
	v_mfma_f32_16x16x32_bf16 v[118:121], v[166:169], v[186:189], v[118:121]
	v_mfma_f32_16x16x32_bf16 v[114:117], v[174:177], v[186:189], v[114:117]
	v_mfma_f32_16x16x32_bf16 v[102:105], v[166:169], v[216:219], v[102:105]
	v_mfma_f32_16x16x32_bf16 v[98:101], v[174:177], v[216:219], v[98:101]
	v_mfma_f32_16x16x32_bf16 v[86:89], v[166:169], v[224:227], v[86:89]
	v_mfma_f32_16x16x32_bf16 v[82:85], v[174:177], v[224:227], v[82:85]
	v_mfma_f32_16x16x32_bf16 v[70:73], v[166:169], v[236:239], v[70:73]
	v_mfma_f32_16x16x32_bf16 v[66:69], v[174:177], v[236:239], v[66:69]
	s_barrier
	s_add_i32 s22, s22, s30
	s_mov_b32 m0, s22
	ds_read_b128 v[182:185], v161 offset:16384
	ds_read_b128 v[186:189], v161 offset:17408
	ds_read_b128 v[190:193], v161 offset:18432
	ds_read_b128 v[216:219], v161 offset:19456
	ds_read_b128 v[220:223], v161 offset:20480
	ds_read_b128 v[224:227], v161 offset:21504
	ds_read_b128 v[228:231], v161 offset:22528
	ds_read_b128 v[236:239], v161 offset:23552
	global_load_lds_dwordx4 v136, vcc
	s_add_i32 m0, s22, 0x2000
	s_add_i32 s22, s23, s30
	global_load_lds_dwordx4 v140, vcc
	s_mov_b32 m0, s22
	s_nop 0
	global_load_lds_dwordx4 v253, vcc
	s_add_i32 m0, s22, 0x2000
	s_nop 0
	global_load_lds_dwordx4 v254, vcc
	s_mov_b32 m0, s31
	s_nop 0
	global_load_lds_dwordx4 v134, s[26:27]
	s_mov_b32 m0, s14
	s_nop 0
	global_load_lds_dwordx4 v138, s[26:27]
	s_waitcnt vmcnt(8)
	s_waitcnt lgkmcnt(0)
	s_barrier
	s_waitcnt lgkmcnt(0)
	v_mfma_f32_16x16x32_bf16 v[62:65], v[130:133], v[182:185], 0
	v_mfma_f32_16x16x32_bf16 v[58:61], v[150:153], v[182:185], 0
	v_mfma_f32_16x16x32_bf16 v[46:49], v[130:133], v[190:193], 0
	v_mfma_f32_16x16x32_bf16 v[42:45], v[150:153], v[190:193], 0
	v_mfma_f32_16x16x32_bf16 v[30:33], v[130:133], v[220:223], 0
	v_mfma_f32_16x16x32_bf16 v[26:29], v[150:153], v[220:223], 0
	v_mfma_f32_16x16x32_bf16 v[14:17], v[130:133], v[228:231], 0
	v_mfma_f32_16x16x32_bf16 v[10:13], v[150:153], v[228:231], 0
	v_mfma_f32_16x16x32_bf16 v[62:65], v[146:149], v[186:189], v[62:65]
	v_mfma_f32_16x16x32_bf16 v[58:61], v[154:157], v[186:189], v[58:61]
	v_mfma_f32_16x16x32_bf16 v[46:49], v[146:149], v[216:219], v[46:49]
	v_mfma_f32_16x16x32_bf16 v[42:45], v[154:157], v[216:219], v[42:45]
	v_mfma_f32_16x16x32_bf16 v[30:33], v[146:149], v[224:227], v[30:33]
	v_mfma_f32_16x16x32_bf16 v[26:29], v[154:157], v[224:227], v[26:29]
	v_mfma_f32_16x16x32_bf16 v[14:17], v[146:149], v[236:239], v[14:17]
	v_mfma_f32_16x16x32_bf16 v[10:13], v[154:157], v[236:239], v[10:13]
	v_mfma_f32_16x16x32_bf16 v[54:57], v[162:165], v[182:185], 0
	v_mfma_f32_16x16x32_bf16 v[50:53], v[170:173], v[182:185], 0
	v_mfma_f32_16x16x32_bf16 v[38:41], v[162:165], v[190:193], 0
	v_mfma_f32_16x16x32_bf16 v[34:37], v[170:173], v[190:193], 0
	v_mfma_f32_16x16x32_bf16 v[22:25], v[162:165], v[220:223], 0
	v_mfma_f32_16x16x32_bf16 v[18:21], v[170:173], v[220:223], 0
	v_mfma_f32_16x16x32_bf16 v[6:9], v[162:165], v[228:231], 0
	v_mfma_f32_16x16x32_bf16 v[2:5], v[170:173], v[228:231], 0
	v_mfma_f32_16x16x32_bf16 v[54:57], v[166:169], v[186:189], v[54:57]
	v_mfma_f32_16x16x32_bf16 v[50:53], v[174:177], v[186:189], v[50:53]
	v_mfma_f32_16x16x32_bf16 v[38:41], v[166:169], v[216:219], v[38:41]
	v_mfma_f32_16x16x32_bf16 v[34:37], v[174:177], v[216:219], v[34:37]
	v_mfma_f32_16x16x32_bf16 v[22:25], v[166:169], v[224:227], v[22:25]
	v_mfma_f32_16x16x32_bf16 v[18:21], v[174:177], v[224:227], v[18:21]
	v_mfma_f32_16x16x32_bf16 v[6:9], v[166:169], v[236:239], v[6:9]
	v_mfma_f32_16x16x32_bf16 v[2:5], v[174:177], v[236:239], v[2:5]
	s_barrier
; #define PG8_STAGE(bufoff, gbase, voff) do { _Pragma("unroll") for (int _i = 0; _i < 2; ++_i) \
;         __builtin_amdgcn_global_load_lds((const unsigned*)((const char*)(gbase) + (voff)[_i]), (LAS unsigned*)(lds + (bufoff) + ldsw + _i * 8192), 16, 0, 0); } while (0)
; #define PG8_LDA(dst, b, h) do { _Pragma("unroll") for (int m = 0; m < 4; ++m) _Pragma("unroll") for (int k = 0; k < 2; ++k) dst[m][k] = *(const LAS bf16x8*)(lds + PG8_SA(b, h) + aoff + m * 2048 + k * 1024); } while (0)
; #define PG8_LDB(dst, b, h) do { _Pragma("unroll") for (int n = 0; n < 2; ++n) _Pragma("unroll") for (int k = 0; k < 2; ++k) dst[n][k] = *(const LAS bf16x8*)(lds + PG8_SB(b, h) + boff + n * 2048 + k * 1024); } while (0)
; #define PG8_MMA(ai, bj, At, Bt) do { __builtin_amdgcn_s_setprio(1); _Pragma("unroll") for (int m = 0; m < 4; ++m) _Pragma("unroll") for (int n = 0; n < 2; ++n) _Pragma("unroll") for (int k = 0; k < 2; ++k) \
;         acc[ai][bj][m][n] = __builtin_amdgcn_mfma_f32_16x16x32_bf16(Bt[n][k], At[m][k], acc[ai][bj][m][n], 0, 0, 0); __builtin_amdgcn_s_setprio(0); } while (0)
; #define PG8_WAIT_V(n) asm volatile("s_waitcnt vmcnt(" #n ")" ::: "memory")
; #define PG8_WAIT_L(n) asm volatile("s_waitcnt lgkmcnt(" #n ")" ::: "memory")
; #define PG8_BAR __builtin_amdgcn_s_barrier()
; #define PG8_SCHED __builtin_amdgcn_sched_barrier(0)
; __device__ __forceinline__ void gemm_phase(LAS unsigned char* lds, const GemmD g, const Sched& S, const Epi& E) {
;     ...
;             PG8_LDB(B0, 1, 0); PG8_LDB(B1, 1, 1); PG8_SCHED; PG8_LDA(At, 1, 0); PG8_STAGE(PG8_SA(0, 1), a2 + hstepA, voffA);
;             PG8_WAIT_V(8); PG8_WAIT_L(0); PG8_BAR; PG8_MMA(0, 0, At, B0); PG8_MMA(0, 1, At, B1); PG8_BAR; PG8_SCHED;
;             PG8_LDA(At, 1, 1); PG8_STAGE(PG8_SB(1, 0), b3, voffB); PG8_STAGE(PG8_SB(1, 1), b3 + hstepB, voffB); PG8_STAGE(PG8_SA(1, 0), a3, voffA);
;             PG8_WAIT_V(8); PG8_WAIT_L(0); PG8_BAR; PG8_MMA(1, 0, At, B0); PG8_MMA(1, 1, At, B1); PG8_BAR; PG8_SCHED;
;         }
	s_add_i32 s22, 0, 0x18000
	s_add_i32 s23, 0, 0x1c000
	ds_read_b128 v[130:133], v242
	ds_read_b128 v[146:149], v242 offset:1024
	ds_read_b128 v[150:153], v242 offset:2048
	ds_read_b128 v[154:157], v242 offset:3072
	ds_read_b128 v[162:165], v243
	ds_read_b128 v[166:169], v243 offset:1024
	ds_read_b128 v[170:173], v243 offset:2048
	ds_read_b128 v[174:177], v243 offset:3072
	s_mov_b32 m0, s15
	ds_read_b128 v[182:185], v161 offset:32768
	ds_read_b128 v[186:189], v161 offset:33792
	ds_read_b128 v[190:193], v161 offset:34816
	ds_read_b128 v[216:219], v161 offset:35840
	ds_read_b128 v[220:223], v161 offset:36864
	ds_read_b128 v[224:227], v161 offset:37888
	ds_read_b128 v[228:231], v161 offset:38912
	ds_read_b128 v[236:239], v161 offset:39936
	global_load_lds_dwordx4 v142, s[26:27]
	s_mov_b32 m0, s10
	s_nop 0
	global_load_lds_dwordx4 v144, s[26:27]
	s_waitcnt vmcnt(8)
	s_waitcnt lgkmcnt(0)
	s_barrier
	s_waitcnt lgkmcnt(0)
	v_mfma_f32_16x16x32_bf16 v[126:129], v[130:133], v[182:185], v[126:129]
	v_mfma_f32_16x16x32_bf16 v[122:125], v[150:153], v[182:185], v[122:125]
	v_mfma_f32_16x16x32_bf16 v[110:113], v[130:133], v[190:193], v[110:113]
	v_mfma_f32_16x16x32_bf16 v[106:109], v[150:153], v[190:193], v[106:109]
	v_mfma_f32_16x16x32_bf16 v[94:97], v[130:133], v[220:223], v[94:97]
	v_mfma_f32_16x16x32_bf16 v[90:93], v[150:153], v[220:223], v[90:93]
	v_mfma_f32_16x16x32_bf16 v[78:81], v[130:133], v[228:231], v[78:81]
	v_mfma_f32_16x16x32_bf16 v[74:77], v[150:153], v[228:231], v[74:77]
	v_mfma_f32_16x16x32_bf16 v[126:129], v[146:149], v[186:189], v[126:129]
	v_mfma_f32_16x16x32_bf16 v[122:125], v[154:157], v[186:189], v[122:125]
	v_mfma_f32_16x16x32_bf16 v[110:113], v[146:149], v[216:219], v[110:113]
	v_mfma_f32_16x16x32_bf16 v[106:109], v[154:157], v[216:219], v[106:109]
	v_mfma_f32_16x16x32_bf16 v[94:97], v[146:149], v[224:227], v[94:97]
	v_mfma_f32_16x16x32_bf16 v[90:93], v[154:157], v[224:227], v[90:93]
	v_mfma_f32_16x16x32_bf16 v[78:81], v[146:149], v[236:239], v[78:81]
	v_mfma_f32_16x16x32_bf16 v[74:77], v[154:157], v[236:239], v[74:77]
	v_mfma_f32_16x16x32_bf16 v[118:121], v[162:165], v[182:185], v[118:121]
	v_mfma_f32_16x16x32_bf16 v[114:117], v[170:173], v[182:185], v[114:117]
	v_mfma_f32_16x16x32_bf16 v[102:105], v[162:165], v[190:193], v[102:105]
	v_mfma_f32_16x16x32_bf16 v[98:101], v[170:173], v[190:193], v[98:101]
	v_mfma_f32_16x16x32_bf16 v[86:89], v[162:165], v[220:223], v[86:89]
	v_mfma_f32_16x16x32_bf16 v[82:85], v[170:173], v[220:223], v[82:85]
	v_mfma_f32_16x16x32_bf16 v[70:73], v[162:165], v[228:231], v[70:73]
	v_mfma_f32_16x16x32_bf16 v[66:69], v[170:173], v[228:231], v[66:69]
	v_mfma_f32_16x16x32_bf16 v[118:121], v[166:169], v[186:189], v[118:121]
	v_mfma_f32_16x16x32_bf16 v[114:117], v[174:177], v[186:189], v[114:117]
	v_mfma_f32_16x16x32_bf16 v[102:105], v[166:169], v[216:219], v[102:105]
	v_mfma_f32_16x16x32_bf16 v[98:101], v[174:177], v[216:219], v[98:101]
	v_mfma_f32_16x16x32_bf16 v[86:89], v[166:169], v[224:227], v[86:89]
	v_mfma_f32_16x16x32_bf16 v[82:85], v[174:177], v[224:227], v[82:85]
	v_mfma_f32_16x16x32_bf16 v[70:73], v[166:169], v[236:239], v[70:73]
	v_mfma_f32_16x16x32_bf16 v[66:69], v[174:177], v[236:239], v[66:69]
	s_barrier
	s_add_i32 s22, s22, s30
	s_add_u32 vcc_lo, vcc_lo, s84
	s_addc_u32 vcc_hi, vcc_hi, s85
	s_add_u32 s26, s26, s84
	s_addc_u32 s27, s27, s85
	s_mov_b32 m0, s22
	ds_read_b128 v[182:185], v161 offset:49152
	ds_read_b128 v[186:189], v161 offset:50176
	ds_read_b128 v[190:193], v161 offset:51200
	ds_read_b128 v[216:219], v161 offset:52224
	ds_read_b128 v[220:223], v161 offset:53248
	ds_read_b128 v[224:227], v161 offset:54272
	ds_read_b128 v[228:231], v161 offset:55296
	ds_read_b128 v[236:239], v161 offset:56320
	global_load_lds_dwordx4 v136, vcc
	s_add_i32 m0, s22, 0x2000
	s_add_i32 s22, s23, s30
	global_load_lds_dwordx4 v140, vcc
	s_mov_b32 m0, s22
	s_nop 0
	global_load_lds_dwordx4 v253, vcc
	s_add_i32 m0, s22, 0x2000
	s_nop 0
	global_load_lds_dwordx4 v254, vcc
	s_mov_b32 m0, s18
	s_nop 0
	global_load_lds_dwordx4 v134, s[26:27]
	s_mov_b32 m0, s19
	s_nop 0
	global_load_lds_dwordx4 v138, s[26:27]
	s_waitcnt vmcnt(8)
	s_waitcnt lgkmcnt(0)
	s_barrier
	s_waitcnt lgkmcnt(0)
	v_mfma_f32_16x16x32_bf16 v[62:65], v[130:133], v[182:185], v[62:65]
	v_mfma_f32_16x16x32_bf16 v[58:61], v[150:153], v[182:185], v[58:61]
	v_mfma_f32_16x16x32_bf16 v[46:49], v[130:133], v[190:193], v[46:49]
	v_mfma_f32_16x16x32_bf16 v[42:45], v[150:153], v[190:193], v[42:45]
	v_mfma_f32_16x16x32_bf16 v[30:33], v[130:133], v[220:223], v[30:33]
	v_mfma_f32_16x16x32_bf16 v[26:29], v[150:153], v[220:223], v[26:29]
	v_mfma_f32_16x16x32_bf16 v[14:17], v[130:133], v[228:231], v[14:17]
	v_mfma_f32_16x16x32_bf16 v[10:13], v[150:153], v[228:231], v[10:13]
	v_mfma_f32_16x16x32_bf16 v[62:65], v[146:149], v[186:189], v[62:65]
	v_mfma_f32_16x16x32_bf16 v[58:61], v[154:157], v[186:189], v[58:61]
	v_mfma_f32_16x16x32_bf16 v[46:49], v[146:149], v[216:219], v[46:49]
	v_mfma_f32_16x16x32_bf16 v[42:45], v[154:157], v[216:219], v[42:45]
	v_mfma_f32_16x16x32_bf16 v[30:33], v[146:149], v[224:227], v[30:33]
	v_mfma_f32_16x16x32_bf16 v[26:29], v[154:157], v[224:227], v[26:29]
	v_mfma_f32_16x16x32_bf16 v[14:17], v[146:149], v[236:239], v[14:17]
	v_mfma_f32_16x16x32_bf16 v[10:13], v[154:157], v[236:239], v[10:13]
	v_mfma_f32_16x16x32_bf16 v[54:57], v[162:165], v[182:185], v[54:57]
	v_mfma_f32_16x16x32_bf16 v[50:53], v[170:173], v[182:185], v[50:53]
	v_mfma_f32_16x16x32_bf16 v[38:41], v[162:165], v[190:193], v[38:41]
	v_mfma_f32_16x16x32_bf16 v[34:37], v[170:173], v[190:193], v[34:37]
	v_mfma_f32_16x16x32_bf16 v[22:25], v[162:165], v[220:223], v[22:25]
	v_mfma_f32_16x16x32_bf16 v[18:21], v[170:173], v[220:223], v[18:21]
	v_mfma_f32_16x16x32_bf16 v[6:9], v[162:165], v[228:231], v[6:9]
	v_mfma_f32_16x16x32_bf16 v[2:5], v[170:173], v[228:231], v[2:5]
	v_mfma_f32_16x16x32_bf16 v[54:57], v[166:169], v[186:189], v[54:57]
	v_mfma_f32_16x16x32_bf16 v[50:53], v[174:177], v[186:189], v[50:53]
	v_mfma_f32_16x16x32_bf16 v[38:41], v[166:169], v[216:219], v[38:41]
	v_mfma_f32_16x16x32_bf16 v[34:37], v[174:177], v[216:219], v[34:37]
	v_mfma_f32_16x16x32_bf16 v[22:25], v[166:169], v[224:227], v[22:25]
	v_mfma_f32_16x16x32_bf16 v[18:21], v[174:177], v[224:227], v[18:21]
	v_mfma_f32_16x16x32_bf16 v[6:9], v[166:169], v[236:239], v[6:9]
	v_mfma_f32_16x16x32_bf16 v[2:5], v[174:177], v[236:239], v[2:5]
	s_barrier
	s_add_u32 s8, s8, 0x100
	s_addc_u32 s9, s9, 0
	s_add_u32 s34, s34, 0x100
	s_addc_u32 s35, s35, 0
	s_cmp_ge_u32 s92, s12
	s_mov_b32 s26, s92
	s_cbranch_scc0 .LBB0_215
	s_branch .Lgemm_after
; #define PG8_STAGE(bufoff, gbase, voff) do { _Pragma("unroll") for (int _i = 0; _i < 2; ++_i) \
;         __builtin_amdgcn_global_load_lds((const unsigned*)((const char*)(gbase) + (voff)[_i]), (LAS unsigned*)(lds + (bufoff) + ldsw + _i * 8192), 16, 0, 0); } while (0)
; #define PG8_LDA(dst, b, h) do { _Pragma("unroll") for (int m = 0; m < 4; ++m) _Pragma("unroll") for (int k = 0; k < 2; ++k) dst[m][k] = *(const LAS bf16x8*)(lds + PG8_SA(b, h) + aoff + m * 2048 + k * 1024); } while (0)
; #define PG8_LDB(dst, b, h) do { _Pragma("unroll") for (int n = 0; n < 2; ++n) _Pragma("unroll") for (int k = 0; k < 2; ++k) dst[n][k] = *(const LAS bf16x8*)(lds + PG8_SB(b, h) + boff + n * 2048 + k * 1024); } while (0)
; #define PG8_MMA(ai, bj, At, Bt) do { __builtin_amdgcn_s_setprio(1); _Pragma("unroll") for (int m = 0; m < 4; ++m) _Pragma("unroll") for (int n = 0; n < 2; ++n) _Pragma("unroll") for (int k = 0; k < 2; ++k) \
;         acc[ai][bj][m][n] = __builtin_amdgcn_mfma_f32_16x16x32_bf16(Bt[n][k], At[m][k], acc[ai][bj][m][n], 0, 0, 0); __builtin_amdgcn_s_setprio(0); } while (0)
; #define PG8_WAIT_V(n) asm volatile("s_waitcnt vmcnt(" #n ")" ::: "memory")
; #define PG8_WAIT_L(n) asm volatile("s_waitcnt lgkmcnt(" #n ")" ::: "memory")
; #define PG8_BAR __builtin_amdgcn_s_barrier()
; #define PG8_SCHED __builtin_amdgcn_sched_barrier(0)
; __device__ __forceinline__ void gemm_phase(LAS unsigned char* lds, const GemmD g, const Sched& S, const Epi& E) {
;     ...
;         for (int t = 0; t < nt; t += 2) {
;             const bool last = (t == nt - 2);
;             const char* a1 = cA + (size_t)(t + 1) * kstep;
;             const char* a2 = last ? nA : cA + (size_t)(t + 2) * kstep; const char* b2 = last ? nB : cB + (size_t)(t + 2) * kstep;
;             const char* a3 = a2 + kstep; const char* b3 = b2 + kstep;
;             PG8_LDB(B0, 0, 0); PG8_LDB(B1, 0, 1); PG8_SCHED; PG8_LDA(At, 0, 0); PG8_STAGE(PG8_SA(1, 1), a1 + hstepA, voffA);
;             PG8_WAIT_V(8); PG8_WAIT_L(0); PG8_BAR; PG8_MMA(0, 0, At, B0); PG8_MMA(0, 1, At, B1); PG8_BAR; PG8_SCHED;
;             PG8_LDA(At, 0, 1); PG8_STAGE(PG8_SB(0, 0), b2, voffB); PG8_STAGE(PG8_SB(0, 1), b2 + hstepB, voffB); PG8_STAGE(PG8_SA(0, 0), a2, voffA);
;             PG8_WAIT_V(8); PG8_WAIT_L(0); PG8_BAR; PG8_MMA(1, 0, At, B0); PG8_MMA(1, 1, At, B1); PG8_BAR; PG8_SCHED;
.LBB0_215:
	ds_read_b128 v[130:133], v240
	ds_read_b128 v[146:149], v240 offset:1024
	ds_read_b128 v[150:153], v240 offset:2048
	ds_read_b128 v[154:157], v240 offset:3072
	ds_read_b128 v[162:165], v241
	ds_read_b128 v[166:169], v241 offset:1024
	ds_read_b128 v[170:173], v241 offset:2048
	ds_read_b128 v[174:177], v241 offset:3072
	s_add_i32 m0, s31, 0xc000
	ds_read_b128 v[182:185], v161
	ds_read_b128 v[186:189], v161 offset:1024
	ds_read_b128 v[190:193], v161 offset:2048
	ds_read_b128 v[216:219], v161 offset:3072
	ds_read_b128 v[220:223], v161 offset:4096
	ds_read_b128 v[224:227], v161 offset:5120
	ds_read_b128 v[228:231], v161 offset:6144
	ds_read_b128 v[236:239], v161 offset:7168
	global_load_lds_dwordx4 v142, s[8:9]
	s_add_i32 m0, s31, 0xe000
	s_nop 0
	global_load_lds_dwordx4 v144, s[8:9]
	s_add_i32 s92, s26, 2
	s_add_u32 s93, s8, 0x80
	s_addc_u32 s27, s9, 0
	s_add_i32 s22, 0, 0x10000
	s_cmp_eq_u32 s11, s26
	s_cselect_b32 s27, s1, s27
	s_cselect_b32 s26, s0, s93
	s_cselect_b32 vcc_hi, s17, s35
	s_cselect_b32 vcc_lo, s16, s34
	s_add_i32 s23, 0, 0x14000
	s_waitcnt vmcnt(8)
	s_waitcnt lgkmcnt(0)
	s_barrier
	s_waitcnt lgkmcnt(0)
	v_mfma_f32_16x16x32_bf16 v[126:129], v[130:133], v[182:185], v[126:129]
	v_mfma_f32_16x16x32_bf16 v[122:125], v[150:153], v[182:185], v[122:125]
	v_mfma_f32_16x16x32_bf16 v[110:113], v[130:133], v[190:193], v[110:113]
	v_mfma_f32_16x16x32_bf16 v[106:109], v[150:153], v[190:193], v[106:109]
	v_mfma_f32_16x16x32_bf16 v[94:97], v[130:133], v[220:223], v[94:97]
	v_mfma_f32_16x16x32_bf16 v[90:93], v[150:153], v[220:223], v[90:93]
	v_mfma_f32_16x16x32_bf16 v[78:81], v[130:133], v[228:231], v[78:81]
	v_mfma_f32_16x16x32_bf16 v[74:77], v[150:153], v[228:231], v[74:77]
	v_mfma_f32_16x16x32_bf16 v[126:129], v[146:149], v[186:189], v[126:129]
	v_mfma_f32_16x16x32_bf16 v[122:125], v[154:157], v[186:189], v[122:125]
	v_mfma_f32_16x16x32_bf16 v[110:113], v[146:149], v[216:219], v[110:113]
	v_mfma_f32_16x16x32_bf16 v[106:109], v[154:157], v[216:219], v[106:109]
	v_mfma_f32_16x16x32_bf16 v[94:97], v[146:149], v[224:227], v[94:97]
	v_mfma_f32_16x16x32_bf16 v[90:93], v[154:157], v[224:227], v[90:93]
	v_mfma_f32_16x16x32_bf16 v[78:81], v[146:149], v[236:239], v[78:81]
	v_mfma_f32_16x16x32_bf16 v[74:77], v[154:157], v[236:239], v[74:77]
	v_mfma_f32_16x16x32_bf16 v[118:121], v[162:165], v[182:185], v[118:121]
	v_mfma_f32_16x16x32_bf16 v[114:117], v[170:173], v[182:185], v[114:117]
	v_mfma_f32_16x16x32_bf16 v[102:105], v[162:165], v[190:193], v[102:105]
	v_mfma_f32_16x16x32_bf16 v[98:101], v[170:173], v[190:193], v[98:101]
	v_mfma_f32_16x16x32_bf16 v[86:89], v[162:165], v[220:223], v[86:89]
	v_mfma_f32_16x16x32_bf16 v[82:85], v[170:173], v[220:223], v[82:85]
	v_mfma_f32_16x16x32_bf16 v[70:73], v[162:165], v[228:231], v[70:73]
	v_mfma_f32_16x16x32_bf16 v[66:69], v[170:173], v[228:231], v[66:69]
	v_mfma_f32_16x16x32_bf16 v[118:121], v[166:169], v[186:189], v[118:121]
	v_mfma_f32_16x16x32_bf16 v[114:117], v[174:177], v[186:189], v[114:117]
	v_mfma_f32_16x16x32_bf16 v[102:105], v[166:169], v[216:219], v[102:105]
	v_mfma_f32_16x16x32_bf16 v[98:101], v[174:177], v[216:219], v[98:101]
	v_mfma_f32_16x16x32_bf16 v[86:89], v[166:169], v[224:227], v[86:89]
	v_mfma_f32_16x16x32_bf16 v[82:85], v[174:177], v[224:227], v[82:85]
	v_mfma_f32_16x16x32_bf16 v[70:73], v[166:169], v[236:239], v[70:73]
	v_mfma_f32_16x16x32_bf16 v[66:69], v[174:177], v[236:239], v[66:69]
	s_barrier
	s_add_i32 s22, s22, s30
	s_mov_b32 m0, s22
	ds_read_b128 v[182:185], v161 offset:16384
	ds_read_b128 v[186:189], v161 offset:17408
	ds_read_b128 v[190:193], v161 offset:18432
	ds_read_b128 v[216:219], v161 offset:19456
	ds_read_b128 v[220:223], v161 offset:20480
	ds_read_b128 v[224:227], v161 offset:21504
	ds_read_b128 v[228:231], v161 offset:22528
	ds_read_b128 v[236:239], v161 offset:23552
	global_load_lds_dwordx4 v136, vcc
	s_add_i32 m0, s22, 0x2000
	s_add_i32 s22, s23, s30
	global_load_lds_dwordx4 v140, vcc
	s_mov_b32 m0, s22
	s_nop 0
	global_load_lds_dwordx4 v253, vcc
	s_add_i32 m0, s22, 0x2000
	s_nop 0
	global_load_lds_dwordx4 v254, vcc
	s_mov_b32 m0, s31
	s_nop 0
	global_load_lds_dwordx4 v134, s[26:27]
	s_mov_b32 m0, s14
	s_nop 0
	global_load_lds_dwordx4 v138, s[26:27]
	s_waitcnt vmcnt(8)
	s_waitcnt lgkmcnt(0)
	s_barrier
	s_waitcnt lgkmcnt(0)
	v_mfma_f32_16x16x32_bf16 v[62:65], v[130:133], v[182:185], v[62:65]
	v_mfma_f32_16x16x32_bf16 v[58:61], v[150:153], v[182:185], v[58:61]
	v_mfma_f32_16x16x32_bf16 v[46:49], v[130:133], v[190:193], v[46:49]
	v_mfma_f32_16x16x32_bf16 v[42:45], v[150:153], v[190:193], v[42:45]
	v_mfma_f32_16x16x32_bf16 v[30:33], v[130:133], v[220:223], v[30:33]
	v_mfma_f32_16x16x32_bf16 v[26:29], v[150:153], v[220:223], v[26:29]
	v_mfma_f32_16x16x32_bf16 v[14:17], v[130:133], v[228:231], v[14:17]
	v_mfma_f32_16x16x32_bf16 v[10:13], v[150:153], v[228:231], v[10:13]
	v_mfma_f32_16x16x32_bf16 v[62:65], v[146:149], v[186:189], v[62:65]
	v_mfma_f32_16x16x32_bf16 v[58:61], v[154:157], v[186:189], v[58:61]
	v_mfma_f32_16x16x32_bf16 v[46:49], v[146:149], v[216:219], v[46:49]
	v_mfma_f32_16x16x32_bf16 v[42:45], v[154:157], v[216:219], v[42:45]
	v_mfma_f32_16x16x32_bf16 v[30:33], v[146:149], v[224:227], v[30:33]
	v_mfma_f32_16x16x32_bf16 v[26:29], v[154:157], v[224:227], v[26:29]
	v_mfma_f32_16x16x32_bf16 v[14:17], v[146:149], v[236:239], v[14:17]
	v_mfma_f32_16x16x32_bf16 v[10:13], v[154:157], v[236:239], v[10:13]
	v_mfma_f32_16x16x32_bf16 v[54:57], v[162:165], v[182:185], v[54:57]
	v_mfma_f32_16x16x32_bf16 v[50:53], v[170:173], v[182:185], v[50:53]
	v_mfma_f32_16x16x32_bf16 v[38:41], v[162:165], v[190:193], v[38:41]
	v_mfma_f32_16x16x32_bf16 v[34:37], v[170:173], v[190:193], v[34:37]
	v_mfma_f32_16x16x32_bf16 v[22:25], v[162:165], v[220:223], v[22:25]
	v_mfma_f32_16x16x32_bf16 v[18:21], v[170:173], v[220:223], v[18:21]
	v_mfma_f32_16x16x32_bf16 v[6:9], v[162:165], v[228:231], v[6:9]
	v_mfma_f32_16x16x32_bf16 v[2:5], v[170:173], v[228:231], v[2:5]
	v_mfma_f32_16x16x32_bf16 v[54:57], v[166:169], v[186:189], v[54:57]
	v_mfma_f32_16x16x32_bf16 v[50:53], v[174:177], v[186:189], v[50:53]
	v_mfma_f32_16x16x32_bf16 v[38:41], v[166:169], v[216:219], v[38:41]
	v_mfma_f32_16x16x32_bf16 v[34:37], v[174:177], v[216:219], v[34:37]
	v_mfma_f32_16x16x32_bf16 v[22:25], v[166:169], v[224:227], v[22:25]
	v_mfma_f32_16x16x32_bf16 v[18:21], v[174:177], v[224:227], v[18:21]
	v_mfma_f32_16x16x32_bf16 v[6:9], v[166:169], v[236:239], v[6:9]
	v_mfma_f32_16x16x32_bf16 v[2:5], v[174:177], v[236:239], v[2:5]
	s_barrier
; #define PG8_STAGE(bufoff, gbase, voff) do { _Pragma("unroll") for (int _i = 0; _i < 2; ++_i) \
;         __builtin_amdgcn_global_load_lds((const unsigned*)((const char*)(gbase) + (voff)[_i]), (LAS unsigned*)(lds + (bufoff) + ldsw + _i * 8192), 16, 0, 0); } while (0)
; #define PG8_LDA(dst, b, h) do { _Pragma("unroll") for (int m = 0; m < 4; ++m) _Pragma("unroll") for (int k = 0; k < 2; ++k) dst[m][k] = *(const LAS bf16x8*)(lds + PG8_SA(b, h) + aoff + m * 2048 + k * 1024); } while (0)
; #define PG8_LDB(dst, b, h) do { _Pragma("unroll") for (int n = 0; n < 2; ++n) _Pragma("unroll") for (int k = 0; k < 2; ++k) dst[n][k] = *(const LAS bf16x8*)(lds + PG8_SB(b, h) + boff + n * 2048 + k * 1024); } while (0)
; #define PG8_MMA(ai, bj, At, Bt) do { __builtin_amdgcn_s_setprio(1); _Pragma("unroll") for (int m = 0; m < 4; ++m) _Pragma("unroll") for (int n = 0; n < 2; ++n) _Pragma("unroll") for (int k = 0; k < 2; ++k) \
;         acc[ai][bj][m][n] = __builtin_amdgcn_mfma_f32_16x16x32_bf16(Bt[n][k], At[m][k], acc[ai][bj][m][n], 0, 0, 0); __builtin_amdgcn_s_setprio(0); } while (0)
; #define PG8_WAIT_V(n) asm volatile("s_waitcnt vmcnt(" #n ")" ::: "memory")
; #define PG8_WAIT_L(n) asm volatile("s_waitcnt lgkmcnt(" #n ")" ::: "memory")
; #define PG8_BAR __builtin_amdgcn_s_barrier()
; #define PG8_SCHED __builtin_amdgcn_sched_barrier(0)
; __device__ __forceinline__ void gemm_phase(LAS unsigned char* lds, const GemmD g, const Sched& S, const Epi& E) {
;     ...
;             PG8_LDB(B0, 1, 0); PG8_LDB(B1, 1, 1); PG8_SCHED; PG8_LDA(At, 1, 0); PG8_STAGE(PG8_SA(0, 1), a2 + hstepA, voffA);
;             PG8_WAIT_V(8); PG8_WAIT_L(0); PG8_BAR; PG8_MMA(0, 0, At, B0); PG8_MMA(0, 1, At, B1); PG8_BAR; PG8_SCHED;
;             PG8_LDA(At, 1, 1); PG8_STAGE(PG8_SB(1, 0), b3, voffB); PG8_STAGE(PG8_SB(1, 1), b3 + hstepB, voffB); PG8_STAGE(PG8_SA(1, 0), a3, voffA);
;             PG8_WAIT_V(8); PG8_WAIT_L(0); PG8_BAR; PG8_MMA(1, 0, At, B0); PG8_MMA(1, 1, At, B1); PG8_BAR; PG8_SCHED;
;         }
	s_add_i32 s22, 0, 0x18000
	s_add_i32 s23, 0, 0x1c000
	ds_read_b128 v[130:133], v242
	ds_read_b128 v[146:149], v242 offset:1024
	ds_read_b128 v[150:153], v242 offset:2048
	ds_read_b128 v[154:157], v242 offset:3072
	ds_read_b128 v[162:165], v243
	ds_read_b128 v[166:169], v243 offset:1024
	ds_read_b128 v[170:173], v243 offset:2048
	ds_read_b128 v[174:177], v243 offset:3072
	s_mov_b32 m0, s15
	ds_read_b128 v[182:185], v161 offset:32768
	ds_read_b128 v[186:189], v161 offset:33792
	ds_read_b128 v[190:193], v161 offset:34816
	ds_read_b128 v[216:219], v161 offset:35840
	ds_read_b128 v[220:223], v161 offset:36864
	ds_read_b128 v[224:227], v161 offset:37888
	ds_read_b128 v[228:231], v161 offset:38912
	ds_read_b128 v[236:239], v161 offset:39936
	global_load_lds_dwordx4 v142, s[26:27]
	s_mov_b32 m0, s10
	s_nop 0
	global_load_lds_dwordx4 v144, s[26:27]
	s_waitcnt vmcnt(8)
	s_waitcnt lgkmcnt(0)
	s_barrier
	s_waitcnt lgkmcnt(0)
	v_mfma_f32_16x16x32_bf16 v[126:129], v[130:133], v[182:185], v[126:129]
	v_mfma_f32_16x16x32_bf16 v[122:125], v[150:153], v[182:185], v[122:125]
	v_mfma_f32_16x16x32_bf16 v[110:113], v[130:133], v[190:193], v[110:113]
	v_mfma_f32_16x16x32_bf16 v[106:109], v[150:153], v[190:193], v[106:109]
	v_mfma_f32_16x16x32_bf16 v[94:97], v[130:133], v[220:223], v[94:97]
	v_mfma_f32_16x16x32_bf16 v[90:93], v[150:153], v[220:223], v[90:93]
	v_mfma_f32_16x16x32_bf16 v[78:81], v[130:133], v[228:231], v[78:81]
	v_mfma_f32_16x16x32_bf16 v[74:77], v[150:153], v[228:231], v[74:77]
	v_mfma_f32_16x16x32_bf16 v[126:129], v[146:149], v[186:189], v[126:129]
	v_mfma_f32_16x16x32_bf16 v[122:125], v[154:157], v[186:189], v[122:125]
	v_mfma_f32_16x16x32_bf16 v[110:113], v[146:149], v[216:219], v[110:113]
	v_mfma_f32_16x16x32_bf16 v[106:109], v[154:157], v[216:219], v[106:109]
	v_mfma_f32_16x16x32_bf16 v[94:97], v[146:149], v[224:227], v[94:97]
	v_mfma_f32_16x16x32_bf16 v[90:93], v[154:157], v[224:227], v[90:93]
	v_mfma_f32_16x16x32_bf16 v[78:81], v[146:149], v[236:239], v[78:81]
	v_mfma_f32_16x16x32_bf16 v[74:77], v[154:157], v[236:239], v[74:77]
	v_mfma_f32_16x16x32_bf16 v[118:121], v[162:165], v[182:185], v[118:121]
	v_mfma_f32_16x16x32_bf16 v[114:117], v[170:173], v[182:185], v[114:117]
	v_mfma_f32_16x16x32_bf16 v[102:105], v[162:165], v[190:193], v[102:105]
	v_mfma_f32_16x16x32_bf16 v[98:101], v[170:173], v[190:193], v[98:101]
	v_mfma_f32_16x16x32_bf16 v[86:89], v[162:165], v[220:223], v[86:89]
	v_mfma_f32_16x16x32_bf16 v[82:85], v[170:173], v[220:223], v[82:85]
	v_mfma_f32_16x16x32_bf16 v[70:73], v[162:165], v[228:231], v[70:73]
	v_mfma_f32_16x16x32_bf16 v[66:69], v[170:173], v[228:231], v[66:69]
	v_mfma_f32_16x16x32_bf16 v[118:121], v[166:169], v[186:189], v[118:121]
	v_mfma_f32_16x16x32_bf16 v[114:117], v[174:177], v[186:189], v[114:117]
	v_mfma_f32_16x16x32_bf16 v[102:105], v[166:169], v[216:219], v[102:105]
	v_mfma_f32_16x16x32_bf16 v[98:101], v[174:177], v[216:219], v[98:101]
	v_mfma_f32_16x16x32_bf16 v[86:89], v[166:169], v[224:227], v[86:89]
	v_mfma_f32_16x16x32_bf16 v[82:85], v[174:177], v[224:227], v[82:85]
	v_mfma_f32_16x16x32_bf16 v[70:73], v[166:169], v[236:239], v[70:73]
	v_mfma_f32_16x16x32_bf16 v[66:69], v[174:177], v[236:239], v[66:69]
	s_barrier
	s_add_i32 s22, s22, s30
	s_add_u32 vcc_lo, vcc_lo, s84
	s_addc_u32 vcc_hi, vcc_hi, s85
	s_add_u32 s26, s26, s84
	s_addc_u32 s27, s27, s85
	s_mov_b32 m0, s22
	ds_read_b128 v[182:185], v161 offset:49152
	ds_read_b128 v[186:189], v161 offset:50176
	ds_read_b128 v[190:193], v161 offset:51200
	ds_read_b128 v[216:219], v161 offset:52224
	ds_read_b128 v[220:223], v161 offset:53248
	ds_read_b128 v[224:227], v161 offset:54272
	ds_read_b128 v[228:231], v161 offset:55296
	ds_read_b128 v[236:239], v161 offset:56320
	global_load_lds_dwordx4 v136, vcc
	s_add_i32 m0, s22, 0x2000
	s_add_i32 s22, s23, s30
	global_load_lds_dwordx4 v140, vcc
	s_mov_b32 m0, s22
	s_nop 0
	global_load_lds_dwordx4 v253, vcc
	s_add_i32 m0, s22, 0x2000
	s_nop 0
	global_load_lds_dwordx4 v254, vcc
	s_mov_b32 m0, s18
	s_nop 0
	global_load_lds_dwordx4 v134, s[26:27]
	s_mov_b32 m0, s19
	s_nop 0
	global_load_lds_dwordx4 v138, s[26:27]
	s_waitcnt vmcnt(8)
	s_waitcnt lgkmcnt(0)
	s_barrier
	s_waitcnt lgkmcnt(0)
	v_mfma_f32_16x16x32_bf16 v[62:65], v[130:133], v[182:185], v[62:65]
	v_mfma_f32_16x16x32_bf16 v[58:61], v[150:153], v[182:185], v[58:61]
	v_mfma_f32_16x16x32_bf16 v[46:49], v[130:133], v[190:193], v[46:49]
	v_mfma_f32_16x16x32_bf16 v[42:45], v[150:153], v[190:193], v[42:45]
	v_mfma_f32_16x16x32_bf16 v[30:33], v[130:133], v[220:223], v[30:33]
	v_mfma_f32_16x16x32_bf16 v[26:29], v[150:153], v[220:223], v[26:29]
	v_mfma_f32_16x16x32_bf16 v[14:17], v[130:133], v[228:231], v[14:17]
	v_mfma_f32_16x16x32_bf16 v[10:13], v[150:153], v[228:231], v[10:13]
	v_mfma_f32_16x16x32_bf16 v[62:65], v[146:149], v[186:189], v[62:65]
	v_mfma_f32_16x16x32_bf16 v[58:61], v[154:157], v[186:189], v[58:61]
	v_mfma_f32_16x16x32_bf16 v[46:49], v[146:149], v[216:219], v[46:49]
	v_mfma_f32_16x16x32_bf16 v[42:45], v[154:157], v[216:219], v[42:45]
	v_mfma_f32_16x16x32_bf16 v[30:33], v[146:149], v[224:227], v[30:33]
	v_mfma_f32_16x16x32_bf16 v[26:29], v[154:157], v[224:227], v[26:29]
	v_mfma_f32_16x16x32_bf16 v[14:17], v[146:149], v[236:239], v[14:17]
	v_mfma_f32_16x16x32_bf16 v[10:13], v[154:157], v[236:239], v[10:13]
	v_mfma_f32_16x16x32_bf16 v[54:57], v[162:165], v[182:185], v[54:57]
	v_mfma_f32_16x16x32_bf16 v[50:53], v[170:173], v[182:185], v[50:53]
	v_mfma_f32_16x16x32_bf16 v[38:41], v[162:165], v[190:193], v[38:41]
	v_mfma_f32_16x16x32_bf16 v[34:37], v[170:173], v[190:193], v[34:37]
	v_mfma_f32_16x16x32_bf16 v[22:25], v[162:165], v[220:223], v[22:25]
	v_mfma_f32_16x16x32_bf16 v[18:21], v[170:173], v[220:223], v[18:21]
	v_mfma_f32_16x16x32_bf16 v[6:9], v[162:165], v[228:231], v[6:9]
	v_mfma_f32_16x16x32_bf16 v[2:5], v[170:173], v[228:231], v[2:5]
	v_mfma_f32_16x16x32_bf16 v[54:57], v[166:169], v[186:189], v[54:57]
	v_mfma_f32_16x16x32_bf16 v[50:53], v[174:177], v[186:189], v[50:53]
	v_mfma_f32_16x16x32_bf16 v[38:41], v[166:169], v[216:219], v[38:41]
	v_mfma_f32_16x16x32_bf16 v[34:37], v[174:177], v[216:219], v[34:37]
	v_mfma_f32_16x16x32_bf16 v[22:25], v[166:169], v[224:227], v[22:25]
	v_mfma_f32_16x16x32_bf16 v[18:21], v[174:177], v[224:227], v[18:21]
	v_mfma_f32_16x16x32_bf16 v[6:9], v[166:169], v[236:239], v[6:9]
	v_mfma_f32_16x16x32_bf16 v[2:5], v[174:177], v[236:239], v[2:5]
	s_barrier
	s_add_u32 s8, s8, 0x100
	s_addc_u32 s9, s9, 0
	s_add_u32 s34, s34, 0x100
	s_addc_u32 s35, s35, 0
	s_cmp_ge_u32 s92, s12
	s_mov_b32 s26, s92
	s_cbranch_scc0 .LBB0_215
